# v20 plus one static s_setprio 1 for waves 4-7 for the duration of the scan unit loop (reset at the phase join)
# speedup vs baseline: 1.0059x; 1.0037x over previous
; __global__ void __launch_bounds__(NTHREADS, 2) fwd_megakernel(Params p) {
;     ...
;             if (G == 256) {
;                 if (bid < 128) {
;                     int nrep = 1;
;     ...
;                     nrep = 3;
;     ...
;                     asm volatile("" : "+s"(nrep));
;                     for (int r3 = 0; r3 < nrep + (g == 0 ? 1 : 0); ++r3) scan_unit(p, g, l, r3 < nrep ? bid : 128 + bid, lds, tidx); }
;                 else { pg8::Gemm gm{ACT, wl + W_PA, Tg, 1024, 1024}; pg8::StaticOrder S; S.init(Tg, 1024, 128, bid - 128); EpiT E{1, g, l, nullptr, nullptr, 0, 1}; pg8::gemm_phase<EpiT>(ldsl, gm, S, E, tidx); }
;             } else {
;                 const int nsu = g == 0 ? 256 : 128;
;                 for (int u = bid; u < nsu; u += G) scan_unit(p, g, l, u, lds, tidx);
;             }
.LBB0_81:
	v_readfirstlane_b32 s100, v252
	s_lshr_b32 s100, s100, 8
	s_cmp_lg_u32 s100, 0
	s_cbranch_scc0 .Lscan_prio_skip
	s_setprio 1

; __global__ void __launch_bounds__(NTHREADS, 2) fwd_megakernel(Params p) {
;     ...
;                     for (int r3 = 0; r3 < nrep + (g == 0 ? 1 : 0); ++r3) scan_unit(p, g, l, r3 < nrep ? bid : 128 + bid, lds, tidx); }
;                 else { pg8::Gemm gm{ACT, wl + W_PA, Tg, 1024, 1024}; pg8::StaticOrder S; S.init(Tg, 1024, 128, bid - 128); EpiT E{1, g, l, nullptr, nullptr, 0, 1}; pg8::gemm_phase<EpiT>(ldsl, gm, S, E, tidx); }
;             } else {
;                 const int nsu = g == 0 ? 256 : 128;
;                 for (int u = bid; u < nsu; u += G) scan_unit(p, g, l, u, lds, tidx);
;             }
;         } else if (kind == 4 && G == 256) { phase_zb(p, g, l, Tg, tidx);
.LBB0_98:
	s_setprio 0
	s_mov_b64 s[0:1], 0
